# baseline (speedup 1.0000x reference)
; #define MFMA(a, b, c) __builtin_amdgcn_mfma_f32_32x32x16_bf16((a), (b), (c), 0, 0, 0)
; template <bool SWAP, int MI>
; DI void gemm_main(const bf16_t* __restrict__ A, int lda, const bf16_t* __restrict__ B, int ldb, int K, char* smem, f32x16 (&acc)[MI][2]) {
;     ...
;     for (int k0 = 0; k0 < K; k0 += 64) {
;         const bool more = (k0 + 64) < K;
;         if (more) {
; #pragma unroll
;             for (int i = 0; i < 2 * MI; ++i) ra[i] = *(const u32x4*)(ap + (size_t)(32 * i) * lda + k0 + 64);
; #pragma unroll
;             for (int i = 0; i < 4; ++i) rb[i] = *(const u32x4*)(bp + (size_t)(32 * i) * ldb + k0 + 64);
;         }
; #pragma unroll
;         for (int s = 0; s < 4; ++s) {
;             bf16x8 af[MI], bfr[2];
; #pragma unroll
;             for (int i = 0; i < MI; ++i) af[i] = *(const bf16x8*)(sA + (wm * (MI * 32) + i * 32 + l31) * GLD + s * 16 + h * 8);
; #pragma unroll
;             for (int j = 0; j < 2; ++j) bfr[j] = *(const bf16x8*)(sB + (wn * 64 + j * 32 + l31) * GLD + s * 16 + h * 8);
; #pragma unroll
;             for (int i = 0; i < MI; ++i)
; #pragma unroll
;                 for (int j = 0; j < 2; ++j) {
;                     if (SWAP) acc[i][j] = MFMA(bfr[j], af[i], acc[i][j]);
;                     else acc[i][j] = MFMA(af[i], bfr[j], acc[i][j]);
;                 }
;         }
;         __syncthreads();
;         if (more) {
; #pragma unroll
;             for (int i = 0; i < 2 * MI; ++i) *(u32x4*)(sA + (lr + 32 * i) * GLD + lc) = ra[i];
; #pragma unroll
;             for (int i = 0; i < 4; ++i) *(u32x4*)(sB + (lr + 32 * i) * GLD + lc) = rb[i];
;         }
;         __syncthreads();
;     }
.LBB0_676:
	s_andn2_b64 vcc, exec, s[10:11]
	s_waitcnt lgkmcnt(0)
	s_barrier
	s_cbranch_vccz .LBB0_672
	ds_read_b128 v[190:193], v189 offset:36864
	ds_read_b128 v[226:229], v187
	ds_read_b128 v[230:233], v189 offset:41472
	ds_read_b128 v[234:237], v187 offset:4608
	ds_read_b128 v[238:241], v187 offset:9216
	ds_read_b128 v[222:225], v188
	ds_read_b128 v[218:221], v189 offset:36896
	ds_read_b128 v[214:217], v189 offset:41504
	s_add_i32 s9, s9, 64
	v_lshl_add_u64 v[180:181], v[180:181], 0, s[4:5]
	v_lshl_add_u64 v[182:183], v[182:183], 0, s[4:5]
	s_branch .Lfl_f1

; #define MFMA(a, b, c) __builtin_amdgcn_mfma_f32_32x32x16_bf16((a), (b), (c), 0, 0, 0)
; template <bool SWAP, int MI>
; DI void gemm_main(const bf16_t* __restrict__ A, int lda, const bf16_t* __restrict__ B, int ldb, int K, char* smem, f32x16 (&acc)[MI][2]) {
;     ...
;     for (int k0 = 0; k0 < K; k0 += 64) {
;         const bool more = (k0 + 64) < K;
;         if (more) {
; #pragma unroll
;             for (int i = 0; i < 2 * MI; ++i) ra[i] = *(const u32x4*)(ap + (size_t)(32 * i) * lda + k0 + 64);
; #pragma unroll
;             for (int i = 0; i < 4; ++i) rb[i] = *(const u32x4*)(bp + (size_t)(32 * i) * ldb + k0 + 64);
;         }
; #pragma unroll
;         for (int s = 0; s < 4; ++s) {
;             bf16x8 af[MI], bfr[2];
; #pragma unroll
;             for (int i = 0; i < MI; ++i) af[i] = *(const bf16x8*)(sA + (wm * (MI * 32) + i * 32 + l31) * GLD + s * 16 + h * 8);
; #pragma unroll
;             for (int j = 0; j < 2; ++j) bfr[j] = *(const bf16x8*)(sB + (wn * 64 + j * 32 + l31) * GLD + s * 16 + h * 8);
; #pragma unroll
;             for (int i = 0; i < MI; ++i)
; #pragma unroll
;                 for (int j = 0; j < 2; ++j) {
;                     if (SWAP) acc[i][j] = MFMA(bfr[j], af[i], acc[i][j]);
;                     else acc[i][j] = MFMA(af[i], bfr[j], acc[i][j]);
;                 }
;         }
;         __syncthreads();
;         if (more) {
; #pragma unroll
;             for (int i = 0; i < 2 * MI; ++i) *(u32x4*)(sA + (lr + 32 * i) * GLD + lc) = ra[i];
; #pragma unroll
;             for (int i = 0; i < 4; ++i) *(u32x4*)(sB + (lr + 32 * i) * GLD + lc) = rb[i];
;         }
;         __syncthreads();
;     }
.LBB0_688:
	s_andn2_b64 vcc, exec, s[8:9]
	s_waitcnt lgkmcnt(0)
	s_barrier
	s_cbranch_vccz .LBB0_693
	ds_read_b128 v[226:229], v193 offset:36864
	ds_read_b128 v[230:233], v191
	ds_read_b128 v[234:237], v193 offset:41472
	ds_read_b128 v[218:221], v191 offset:4608
	ds_read_b128 v[214:217], v191 offset:9216
	ds_read_b128 v[210:213], v192
	ds_read_b128 v[238:241], v193 offset:36896
	ds_read_b128 v[222:225], v193 offset:41504
	s_add_i32 s21, s21, 64
	v_lshl_add_u64 v[186:187], v[186:187], 0, s[4:5]
	v_lshl_add_u64 v[188:189], v[188:189], 0, s[4:5]
	s_branch .Lfl_f2

; #define MFMA(a, b, c) __builtin_amdgcn_mfma_f32_32x32x16_bf16((a), (b), (c), 0, 0, 0)
; template <bool SWAP, int MI>
; DI void gemm_main(const bf16_t* __restrict__ A, int lda, const bf16_t* __restrict__ B, int ldb, int K, char* smem, f32x16 (&acc)[MI][2]) {
;     ...
;     for (int k0 = 0; k0 < K; k0 += 64) {
;         const bool more = (k0 + 64) < K;
;         if (more) {
; #pragma unroll
;             for (int i = 0; i < 2 * MI; ++i) ra[i] = *(const u32x4*)(ap + (size_t)(32 * i) * lda + k0 + 64);
; #pragma unroll
;             for (int i = 0; i < 4; ++i) rb[i] = *(const u32x4*)(bp + (size_t)(32 * i) * ldb + k0 + 64);
;         }
; #pragma unroll
;         for (int s = 0; s < 4; ++s) {
;             bf16x8 af[MI], bfr[2];
; #pragma unroll
;             for (int i = 0; i < MI; ++i) af[i] = *(const bf16x8*)(sA + (wm * (MI * 32) + i * 32 + l31) * GLD + s * 16 + h * 8);
; #pragma unroll
;             for (int j = 0; j < 2; ++j) bfr[j] = *(const bf16x8*)(sB + (wn * 64 + j * 32 + l31) * GLD + s * 16 + h * 8);
; #pragma unroll
;             for (int i = 0; i < MI; ++i)
; #pragma unroll
;                 for (int j = 0; j < 2; ++j) {
;                     if (SWAP) acc[i][j] = MFMA(bfr[j], af[i], acc[i][j]);
;                     else acc[i][j] = MFMA(af[i], bfr[j], acc[i][j]);
;                 }
;         }
;         __syncthreads();
;         if (more) {
; #pragma unroll
;             for (int i = 0; i < 2 * MI; ++i) *(u32x4*)(sA + (lr + 32 * i) * GLD + lc) = ra[i];
; #pragma unroll
;             for (int i = 0; i < 4; ++i) *(u32x4*)(sB + (lr + 32 * i) * GLD + lc) = rb[i];
;         }
;         __syncthreads();
;     }
.LBB0_706:
	s_andn2_b64 vcc, exec, s[12:13]
	s_waitcnt lgkmcnt(0)
	s_barrier
	s_cbranch_vccz .LBB0_711
	ds_read_b128 v[192:195], v191 offset:36864
	ds_read_b128 v[226:229], v189
	ds_read_b128 v[230:233], v191 offset:41472
	ds_read_b128 v[222:225], v189 offset:4608
	ds_read_b128 v[218:221], v189 offset:9216
	ds_read_b128 v[214:217], v190
	ds_read_b128 v[234:237], v191 offset:36896
	ds_read_b128 v[238:241], v191 offset:41504
	s_add_i32 s11, s11, 64
	v_lshl_add_u64 v[186:187], v[186:187], 0, s[4:5]
	v_lshl_add_u64 v[184:185], v[184:185], 0, s[4:5]
	s_branch .Lfl_g2

; #define MFMA(a, b, c) __builtin_amdgcn_mfma_f32_32x32x16_bf16((a), (b), (c), 0, 0, 0)
; template <bool SWAP, int MI>
; DI void gemm_main(const bf16_t* __restrict__ A, int lda, const bf16_t* __restrict__ B, int ldb, int K, char* smem, f32x16 (&acc)[MI][2]) {
;     ...
;     for (int k0 = 0; k0 < K; k0 += 64) {
;         const bool more = (k0 + 64) < K;
;         if (more) {
; #pragma unroll
;             for (int i = 0; i < 2 * MI; ++i) ra[i] = *(const u32x4*)(ap + (size_t)(32 * i) * lda + k0 + 64);
; #pragma unroll
;             for (int i = 0; i < 4; ++i) rb[i] = *(const u32x4*)(bp + (size_t)(32 * i) * ldb + k0 + 64);
;         }
; #pragma unroll
;         for (int s = 0; s < 4; ++s) {
;             bf16x8 af[MI], bfr[2];
; #pragma unroll
;             for (int i = 0; i < MI; ++i) af[i] = *(const bf16x8*)(sA + (wm * (MI * 32) + i * 32 + l31) * GLD + s * 16 + h * 8);
; #pragma unroll
;             for (int j = 0; j < 2; ++j) bfr[j] = *(const bf16x8*)(sB + (wn * 64 + j * 32 + l31) * GLD + s * 16 + h * 8);
; #pragma unroll
;             for (int i = 0; i < MI; ++i)
; #pragma unroll
;                 for (int j = 0; j < 2; ++j) {
;                     if (SWAP) acc[i][j] = MFMA(bfr[j], af[i], acc[i][j]);
;                     else acc[i][j] = MFMA(af[i], bfr[j], acc[i][j]);
;                 }
;         }
;         __syncthreads();
;         if (more) {
; #pragma unroll
;             for (int i = 0; i < 2 * MI; ++i) *(u32x4*)(sA + (lr + 32 * i) * GLD + lc) = ra[i];
; #pragma unroll
;             for (int i = 0; i < 4; ++i) *(u32x4*)(sB + (lr + 32 * i) * GLD + lc) = rb[i];
;         }
;         __syncthreads();
;     }
.LBB0_1722:
	s_andn2_b64 vcc, exec, s[0:1]
	s_waitcnt lgkmcnt(0)
	s_barrier
	s_cbranch_vccz .LBB0_1727
	ds_read_b128 v[186:189], v185 offset:36864
	ds_read_b128 v[190:193], v183
	ds_read_b128 v[226:229], v185 offset:41472
	ds_read_b128 v[238:241], v183 offset:4608
	ds_read_b128 v[222:225], v183 offset:9216
	ds_read_b128 v[218:221], v184
	ds_read_b128 v[230:233], v185 offset:36896
	ds_read_b128 v[234:237], v185 offset:41504
	s_add_i32 s9, s9, 64
	v_lshl_add_u64 v[178:179], v[178:179], 0, s[4:5]
	v_lshl_add_u64 v[180:181], v[180:181], 0, s[4:5]
	s_branch .Lfl_g1ea

; #define MFMA(a, b, c) __builtin_amdgcn_mfma_f32_32x32x16_bf16((a), (b), (c), 0, 0, 0)
; template <bool SWAP, int MI>
; DI void gemm_main(const bf16_t* __restrict__ A, int lda, const bf16_t* __restrict__ B, int ldb, int K, char* smem, f32x16 (&acc)[MI][2]) {
;     ...
;     for (int k0 = 0; k0 < K; k0 += 64) {
;         const bool more = (k0 + 64) < K;
;         if (more) {
; #pragma unroll
;             for (int i = 0; i < 2 * MI; ++i) ra[i] = *(const u32x4*)(ap + (size_t)(32 * i) * lda + k0 + 64);
; #pragma unroll
;             for (int i = 0; i < 4; ++i) rb[i] = *(const u32x4*)(bp + (size_t)(32 * i) * ldb + k0 + 64);
;         }
; #pragma unroll
;         for (int s = 0; s < 4; ++s) {
;             bf16x8 af[MI], bfr[2];
; #pragma unroll
;             for (int i = 0; i < MI; ++i) af[i] = *(const bf16x8*)(sA + (wm * (MI * 32) + i * 32 + l31) * GLD + s * 16 + h * 8);
; #pragma unroll
;             for (int j = 0; j < 2; ++j) bfr[j] = *(const bf16x8*)(sB + (wn * 64 + j * 32 + l31) * GLD + s * 16 + h * 8);
; #pragma unroll
;             for (int i = 0; i < MI; ++i)
; #pragma unroll
;                 for (int j = 0; j < 2; ++j) {
;                     if (SWAP) acc[i][j] = MFMA(bfr[j], af[i], acc[i][j]);
;                     else acc[i][j] = MFMA(af[i], bfr[j], acc[i][j]);
;                 }
;         }
;         __syncthreads();
;         if (more) {
; #pragma unroll
;             for (int i = 0; i < 2 * MI; ++i) *(u32x4*)(sA + (lr + 32 * i) * GLD + lc) = ra[i];
; #pragma unroll
;             for (int i = 0; i < 4; ++i) *(u32x4*)(sB + (lr + 32 * i) * GLD + lc) = rb[i];
;         }
;         __syncthreads();
;     }
.LBB0_1738:
	s_andn2_b64 vcc, exec, s[0:1]
	s_waitcnt lgkmcnt(0)
	s_barrier
	s_cbranch_vccz .LBB0_1743
	ds_read_b128 v[190:193], v185 offset:36864
	ds_read_b128 v[186:189], v183
	ds_read_b128 v[226:229], v185 offset:41472
	ds_read_b128 v[238:241], v183 offset:4608
	ds_read_b128 v[222:225], v183 offset:9216
	ds_read_b128 v[218:221], v184
	ds_read_b128 v[230:233], v185 offset:36896
	ds_read_b128 v[234:237], v185 offset:41504
	s_add_i32 s9, s9, 64
	v_lshl_add_u64 v[178:179], v[178:179], 0, s[4:5]
	v_lshl_add_u64 v[180:181], v[180:181], 0, s[4:5]
	s_branch .Lfl_g1eb
